# row-panel RMS exchange poll loop: s_sleep 2 shortened to s_sleep 1 (3 sites), otherwise v36
# baseline (speedup 1.0000x reference)
.LBB0_555:
	global_load_dword v3, v197, s[36:37] sc1
	s_mov_b64 s[86:87], -1
	s_waitcnt vmcnt(0)
	v_readfirstlane_b32 s4, v3
	s_cmp_gt_u32 s4, 63
	s_mov_b64 s[4:5], -1
	s_cbranch_scc1 .LBB0_554
	s_memrealtime s[4:5]
	s_waitcnt lgkmcnt(0)
	s_sub_u32 s4, s4, s56
	s_subb_u32 s5, s5, s57
	v_cmp_lt_u64_e32 vcc, s[4:5], v[222:223]
	s_mov_b64 s[4:5], -1
	s_cbranch_vccz .LBB0_553
	s_mov_b64 s[4:5], 0
	s_sleep 1
	s_branch .LBB0_553

.LBB0_1078:
	global_load_dword v3, v197, s[82:83] sc1
	s_mov_b64 s[84:85], -1
	s_mov_b64 s[86:87], -1
	s_waitcnt vmcnt(0)
	v_readfirstlane_b32 s4, v3
	s_cmp_gt_u32 s4, 63
	s_cbranch_scc1 .LBB0_1077
	s_memrealtime s[4:5]
	s_waitcnt lgkmcnt(0)
	s_sub_u32 s4, s4, s56
	s_subb_u32 s5, s5, s57
	v_cmp_lt_u64_e32 vcc, s[4:5], v[222:223]
	s_cbranch_vccz .LBB0_1076
	s_mov_b64 s[86:87], 0
	s_sleep 1
	s_branch .LBB0_1076

.LBB0_1454:
	global_load_dword v3, v197, s[74:75] sc1
	s_mov_b64 s[80:81], -1
	s_waitcnt vmcnt(0)
	v_readfirstlane_b32 s4, v3
	s_cmp_gt_u32 s4, 63
	s_mov_b64 s[4:5], -1
	s_cbranch_scc1 .LBB0_1453
	s_memrealtime s[4:5]
	s_waitcnt lgkmcnt(0)
	s_sub_u32 s4, s4, s56
	s_subb_u32 s5, s5, s57
	v_cmp_lt_u64_e32 vcc, s[4:5], v[222:223]
	s_mov_b64 s[4:5], -1
	s_cbranch_vccz .LBB0_1452
	s_mov_b64 s[4:5], 0
	s_sleep 1
	s_branch .LBB0_1452
